# v17: v16 + layer-1 FFN weight conversion (blocks 120-255 of the l0 up phase) as pipelined passes
# speedup vs baseline: 1.0085x; 1.0011x over previous
.LBB0_1493:
	s_add_i32 s8, s30, 0xffffff88
	s_cmpk_gt_u32 s8, 0x87
	s_cselect_b64 s[2:3], -1, 0
	s_xor_b64 s[4:5], s[36:37], -1
	s_or_b64 s[2:3], s[2:3], s[4:5]
	s_and_b64 vcc, exec, s[2:3]
	s_cbranch_vccnz .LBB0_1558
	v_mov_b32_e32 v1, 0
	ds_read_b64 v[2:3], v1 offset:416
	ds_read_b64 v[4:5], v1 offset:184
	ds_read_b64 v[6:7], v1 offset:208
	s_waitcnt lgkmcnt(0)
	v_readfirstlane_b32 s14, v2
	v_readfirstlane_b32 s15, v3
	v_readfirstlane_b32 s6, v4
	v_readfirstlane_b32 s7, v5
	v_readfirstlane_b32 s8, v6
	v_readfirstlane_b32 s9, v7
	v_lshrrev_b32_e32 v163, 4, v0
	v_and_b32_e32 v164, 15, v0
	v_lshlrev_b32_e32 v164, 4, v164
	v_mul_u32_u24_e32 v146, 0x104, v163
	v_add_u32_e32 v146, v146, v164
	v_add_u32_e32 v146, 0x400, v146
	v_lshrrev_b32_e32 v165, 3, v0
	v_and_b32_e32 v166, 7, v0
	v_lshlrev_b32_e32 v166, 3, v166
	v_mul_u32_u24_e32 v147, 0x104, v166
	v_lshlrev_b32_e32 v167, 2, v165
	v_add_u32_e32 v147, v147, v167
	v_add_u32_e32 v147, 0x400, v147
	v_lshl_add_u32 v157, v163, 12, v164
	v_add_u32_e32 v158, 0x20000, v157
	v_mul_u32_u24_e32 v159, 0x5800, v163
	v_add_u32_e32 v159, v159, v164
	v_add_u32_e32 v160, 0xb0000, v159
	v_lshlrev_b32_e32 v167, 1, v166
	v_lshl_add_u32 v161, v165, 11, v167
	v_mul_u32_u24_e32 v162, 0x1600, v165
	v_add_u32_e32 v162, v162, v167
	s_add_u32 s6, s6, 0x1600000
	s_addc_u32 s7, s7, 0
	s_add_u32 s8, s8, 0xb00000
	s_addc_u32 s9, s9, 0
	s_add_u32 s10, s14, 0x13c8000
	s_addc_u32 s11, s15, 0
	s_add_u32 s12, s14, 0x2448000
	s_addc_u32 s13, s15, 0
	s_add_i32 s4, s30, 0xffffff88
	s_add_i32 s5, s4, 88
	s_cmp_ge_u32 s5, 136
	s_cselect_b32 s24, 136, 0
	s_sub_i32 s5, s5, s24
	s_add_i32 s16, s4, 0
	s_and_b32 s17, s16, 15
	s_lshr_b32 s18, s16, 4
	s_mul_i32 s17, s17, 1441792
	s_lshl_b32 s18, s18, 8
	s_add_u32 s17, s17, s18
	s_add_u32 s20, s6, s17
	s_addc_u32 s21, s7, 0
	global_load_dwordx4 v[2:5], v159, s[20:21]
	global_load_dwordx4 v[6:9], v160, s[20:21]
	s_add_i32 s16, s4, 136
	s_and_b32 s17, s16, 15
	s_lshr_b32 s18, s16, 4
	s_mul_i32 s17, s17, 1441792
	s_lshl_b32 s18, s18, 8
	s_add_u32 s17, s17, s18
	s_add_u32 s20, s6, s17
	s_addc_u32 s21, s7, 0
	global_load_dwordx4 v[10:13], v159, s[20:21]
	global_load_dwordx4 v[14:17], v160, s[20:21]
	s_add_i32 s16, s4, 272
	s_and_b32 s17, s16, 15
	s_lshr_b32 s18, s16, 4
	s_mul_i32 s17, s17, 1441792
	s_lshl_b32 s18, s18, 8
	s_add_u32 s17, s17, s18
	s_add_u32 s20, s6, s17
	s_addc_u32 s21, s7, 0
	global_load_dwordx4 v[18:21], v159, s[20:21]
	global_load_dwordx4 v[22:25], v160, s[20:21]
	s_add_i32 s16, s4, 408
	s_and_b32 s17, s16, 15
	s_lshr_b32 s18, s16, 4
	s_mul_i32 s17, s17, 1441792
	s_lshl_b32 s18, s18, 8
	s_add_u32 s17, s17, s18
	s_add_u32 s20, s6, s17
	s_addc_u32 s21, s7, 0
	global_load_dwordx4 v[26:29], v159, s[20:21]
	global_load_dwordx4 v[30:33], v160, s[20:21]
	s_add_i32 s16, s4, 544
	s_and_b32 s17, s16, 15
	s_lshr_b32 s18, s16, 4
	s_mul_i32 s17, s17, 1441792
	s_lshl_b32 s18, s18, 8
	s_add_u32 s17, s17, s18
	s_add_u32 s20, s6, s17
	s_addc_u32 s21, s7, 0
	global_load_dwordx4 v[34:37], v159, s[20:21]
	global_load_dwordx4 v[38:41], v160, s[20:21]
	s_add_i32 s16, s4, 680
	s_and_b32 s17, s16, 15
	s_lshr_b32 s18, s16, 4
	s_mul_i32 s17, s17, 1441792
	s_lshl_b32 s18, s18, 8
	s_add_u32 s17, s17, s18
	s_add_u32 s20, s6, s17
	s_addc_u32 s21, s7, 0
	global_load_dwordx4 v[42:45], v159, s[20:21]
	global_load_dwordx4 v[46:49], v160, s[20:21]
	s_add_i32 s16, s4, 816
	s_and_b32 s17, s16, 15
	s_lshr_b32 s18, s16, 4
	s_mul_i32 s17, s17, 1441792
	s_lshl_b32 s18, s18, 8
	s_add_u32 s17, s17, s18
	s_add_u32 s20, s6, s17
	s_addc_u32 s21, s7, 0
	global_load_dwordx4 v[50:53], v159, s[20:21]
	global_load_dwordx4 v[54:57], v160, s[20:21]
	s_add_i32 s16, s4, 952
	s_and_b32 s17, s16, 15
	s_lshr_b32 s18, s16, 4
	s_mul_i32 s17, s17, 1441792
	s_lshl_b32 s18, s18, 8
	s_add_u32 s17, s17, s18
	s_add_u32 s20, s6, s17
	s_addc_u32 s21, s7, 0
	global_load_dwordx4 v[58:61], v159, s[20:21]
	global_load_dwordx4 v[62:65], v160, s[20:21]
	s_add_i32 s16, s4, 1088
	s_and_b32 s17, s16, 15
	s_lshr_b32 s18, s16, 4
	s_mul_i32 s17, s17, 1441792
	s_lshl_b32 s18, s18, 8
	s_add_u32 s17, s17, s18
	s_add_u32 s20, s6, s17
	s_addc_u32 s21, s7, 0
	global_load_dwordx4 v[66:69], v159, s[20:21]
	global_load_dwordx4 v[70:73], v160, s[20:21]
	s_add_i32 s16, s4, 1224
	s_and_b32 s17, s16, 15
	s_lshr_b32 s18, s16, 4
	s_mul_i32 s17, s17, 1441792
	s_lshl_b32 s18, s18, 8
	s_add_u32 s17, s17, s18
	s_add_u32 s20, s6, s17
	s_addc_u32 s21, s7, 0
	global_load_dwordx4 v[74:77], v159, s[20:21]
	global_load_dwordx4 v[78:81], v160, s[20:21]
	s_add_i32 s16, s4, 1360
	s_add_i32 s19, s4, 1088
	s_cmp_lt_u32 s16, 1408
	s_cselect_b32 s16, s16, s19
	s_and_b32 s17, s16, 15
	s_lshr_b32 s18, s16, 4
	s_mul_i32 s17, s17, 1441792
	s_lshl_b32 s18, s18, 8
	s_add_u32 s17, s17, s18
	s_add_u32 s20, s6, s17
	s_addc_u32 s21, s7, 0
	global_load_dwordx4 v[82:85], v159, s[20:21]
	global_load_dwordx4 v[86:89], v160, s[20:21]
	s_waitcnt vmcnt(14)
	v_add_u32_e32 v148, 0x0, v146
	ds_write2_b32 v148, v2, v3 offset1:1
	ds_write2_b32 v148, v4, v5 offset0:2 offset1:3
	v_add_u32_e32 v148, 0x2080, v146
	ds_write2_b32 v148, v6, v7 offset1:1
	ds_write2_b32 v148, v8, v9 offset0:2 offset1:3
	v_add_u32_e32 v148, 0x4100, v146
	ds_write2_b32 v148, v10, v11 offset1:1
	ds_write2_b32 v148, v12, v13 offset0:2 offset1:3
	v_add_u32_e32 v148, 0x6180, v146
	ds_write2_b32 v148, v14, v15 offset1:1
	ds_write2_b32 v148, v16, v17 offset0:2 offset1:3
	v_add_u32_e32 v148, 0x8200, v146
	ds_write2_b32 v148, v18, v19 offset1:1
	ds_write2_b32 v148, v20, v21 offset0:2 offset1:3
	v_add_u32_e32 v148, 0xa280, v146
	ds_write2_b32 v148, v22, v23 offset1:1
	ds_write2_b32 v148, v24, v25 offset0:2 offset1:3
	v_add_u32_e32 v148, 0xc300, v146
	ds_write2_b32 v148, v26, v27 offset1:1
	ds_write2_b32 v148, v28, v29 offset0:2 offset1:3
	v_add_u32_e32 v148, 0xe380, v146
	ds_write2_b32 v148, v30, v31 offset1:1
	ds_write2_b32 v148, v32, v33 offset0:2 offset1:3
	s_waitcnt lgkmcnt(0)
	s_add_i32 s16, s5, 0
	s_mul_i32 s18, s16, 1490
	s_lshr_b32 s18, s18, 16
	s_mul_i32 s17, s18, 44
	s_sub_i32 s17, s16, s17
	s_mul_i32 s17, s17, 262144
	s_lshl_b32 s18, s18, 8
	s_add_u32 s17, s17, s18
	s_add_u32 s20, s8, s17
	s_addc_u32 s21, s9, 0
	global_load_dwordx4 v[2:5], v157, s[20:21]
	global_load_dwordx4 v[6:9], v158, s[20:21]
	s_add_i32 s16, s5, 136
	s_mul_i32 s18, s16, 1490
	s_lshr_b32 s18, s18, 16
	s_mul_i32 s17, s18, 44
	s_sub_i32 s17, s16, s17
	s_mul_i32 s17, s17, 262144
	s_lshl_b32 s18, s18, 8
	s_add_u32 s17, s17, s18
	s_add_u32 s20, s8, s17
	s_addc_u32 s21, s9, 0
	global_load_dwordx4 v[10:13], v157, s[20:21]
	global_load_dwordx4 v[14:17], v158, s[20:21]
	s_add_i32 s16, s5, 272
	s_mul_i32 s18, s16, 1490
	s_lshr_b32 s18, s18, 16
	s_mul_i32 s17, s18, 44
	s_sub_i32 s17, s16, s17
	s_mul_i32 s17, s17, 262144
	s_lshl_b32 s18, s18, 8
	s_add_u32 s17, s17, s18
	s_add_u32 s20, s8, s17
	s_addc_u32 s21, s9, 0
	global_load_dwordx4 v[18:21], v157, s[20:21]
	global_load_dwordx4 v[22:25], v158, s[20:21]
	s_add_i32 s16, s5, 408
	s_mul_i32 s18, s16, 1490
	s_lshr_b32 s18, s18, 16
	s_mul_i32 s17, s18, 44
	s_sub_i32 s17, s16, s17
	s_mul_i32 s17, s17, 262144
	s_lshl_b32 s18, s18, 8
	s_add_u32 s17, s17, s18
	s_add_u32 s20, s8, s17
	s_addc_u32 s21, s9, 0
	global_load_dwordx4 v[26:29], v157, s[20:21]
	global_load_dwordx4 v[30:33], v158, s[20:21]
	s_barrier
	v_add_u32_e32 v149, 0x0, v147
	v_add_u32_e32 v150, 0x400, v147
	ds_read2_b32 v[98:99], v149 offset1:65
	ds_read2_b32 v[100:101], v149 offset0:130 offset1:195
	ds_read2_b32 v[102:103], v150 offset0:4 offset1:69
	ds_read2_b32 v[104:105], v150 offset0:134 offset1:199
	v_add_u32_e32 v151, 0x4100, v147
	v_add_u32_e32 v152, 0x4500, v147
	ds_read2_b32 v[106:107], v151 offset1:65
	ds_read2_b32 v[108:109], v151 offset0:130 offset1:195
	ds_read2_b32 v[110:111], v152 offset0:4 offset1:69
	ds_read2_b32 v[112:113], v152 offset0:134 offset1:199
	v_add_u32_e32 v153, 0x8200, v147
	v_add_u32_e32 v154, 0x8600, v147
	ds_read2_b32 v[114:115], v153 offset1:65
	ds_read2_b32 v[116:117], v153 offset0:130 offset1:195
	ds_read2_b32 v[118:119], v154 offset0:4 offset1:69
	ds_read2_b32 v[120:121], v154 offset0:134 offset1:199
	v_add_u32_e32 v155, 0xc300, v147
	v_add_u32_e32 v156, 0xc700, v147
	ds_read2_b32 v[122:123], v155 offset1:65
	ds_read2_b32 v[124:125], v155 offset0:130 offset1:195
	ds_read2_b32 v[126:127], v156 offset0:4 offset1:69
	ds_read2_b32 v[128:129], v156 offset0:134 offset1:199
	s_add_i32 s16, s4, 0
	s_and_b32 s17, s16, 15
	s_lshr_b32 s18, s16, 4
	s_sub_i32 s23, s18, 44
	s_cmp_lt_u32 s18, 44
	s_cselect_b32 s22, s18, s23
	s_cselect_b32 s23, 0, 0x80
	s_lshr_b32 s18, s22, 1
	s_lshl_b32 s18, s18, 8
	s_and_b32 s22, s22, 1
	s_lshl_b32 s22, s22, 6
	s_add_i32 s22, s22, s18
	s_add_i32 s22, s22, s23
	s_mul_i32 s22, s22, 2048
	s_lshl_b32 s17, s17, 7
	s_add_u32 s22, s22, s17
	s_add_u32 s20, s10, s22
	s_addc_u32 s21, s11, 0
	s_waitcnt lgkmcnt(12)
	v_cvt_pk_bf16_f32 v130, v98, v99
	v_cvt_pk_bf16_f32 v131, v100, v101
	v_cvt_pk_bf16_f32 v132, v102, v103
	v_cvt_pk_bf16_f32 v133, v104, v105
	global_store_dwordx4 v161, v[130:133], s[20:21] sc1
	s_add_i32 s16, s4, 136
	s_and_b32 s17, s16, 15
	s_lshr_b32 s18, s16, 4
	s_sub_i32 s23, s18, 44
	s_cmp_lt_u32 s18, 44
	s_cselect_b32 s22, s18, s23
	s_cselect_b32 s23, 0, 0x80
	s_lshr_b32 s18, s22, 1
	s_lshl_b32 s18, s18, 8
	s_and_b32 s22, s22, 1
	s_lshl_b32 s22, s22, 6
	s_add_i32 s22, s22, s18
	s_add_i32 s22, s22, s23
	s_mul_i32 s22, s22, 2048
	s_lshl_b32 s17, s17, 7
	s_add_u32 s22, s22, s17
	s_add_u32 s20, s10, s22
	s_addc_u32 s21, s11, 0
	s_waitcnt lgkmcnt(8)
	v_cvt_pk_bf16_f32 v134, v106, v107
	v_cvt_pk_bf16_f32 v135, v108, v109
	v_cvt_pk_bf16_f32 v136, v110, v111
	v_cvt_pk_bf16_f32 v137, v112, v113
	global_store_dwordx4 v161, v[134:137], s[20:21] sc1
	s_add_i32 s16, s4, 272
	s_and_b32 s17, s16, 15
	s_lshr_b32 s18, s16, 4
	s_sub_i32 s23, s18, 44
	s_cmp_lt_u32 s18, 44
	s_cselect_b32 s22, s18, s23
	s_cselect_b32 s23, 0, 0x80
	s_lshr_b32 s18, s22, 1
	s_lshl_b32 s18, s18, 8
	s_and_b32 s22, s22, 1
	s_lshl_b32 s22, s22, 6
	s_add_i32 s22, s22, s18
	s_add_i32 s22, s22, s23
	s_mul_i32 s22, s22, 2048
	s_lshl_b32 s17, s17, 7
	s_add_u32 s22, s22, s17
	s_add_u32 s20, s10, s22
	s_addc_u32 s21, s11, 0
	s_waitcnt lgkmcnt(4)
	v_cvt_pk_bf16_f32 v138, v114, v115
	v_cvt_pk_bf16_f32 v139, v116, v117
	v_cvt_pk_bf16_f32 v140, v118, v119
	v_cvt_pk_bf16_f32 v141, v120, v121
	global_store_dwordx4 v161, v[138:141], s[20:21] sc1
	s_add_i32 s16, s4, 408
	s_and_b32 s17, s16, 15
	s_lshr_b32 s18, s16, 4
	s_sub_i32 s23, s18, 44
	s_cmp_lt_u32 s18, 44
	s_cselect_b32 s22, s18, s23
	s_cselect_b32 s23, 0, 0x80
	s_lshr_b32 s18, s22, 1
	s_lshl_b32 s18, s18, 8
	s_and_b32 s22, s22, 1
	s_lshl_b32 s22, s22, 6
	s_add_i32 s22, s22, s18
	s_add_i32 s22, s22, s23
	s_mul_i32 s22, s22, 2048
	s_lshl_b32 s17, s17, 7
	s_add_u32 s22, s22, s17
	s_add_u32 s20, s10, s22
	s_addc_u32 s21, s11, 0
	s_waitcnt lgkmcnt(0)
	v_cvt_pk_bf16_f32 v142, v122, v123
	v_cvt_pk_bf16_f32 v143, v124, v125
	v_cvt_pk_bf16_f32 v144, v126, v127
	v_cvt_pk_bf16_f32 v145, v128, v129
	global_store_dwordx4 v161, v[142:145], s[20:21] sc1
	s_waitcnt vmcnt(18)
	v_add_u32_e32 v148, 0x10400, v146
	ds_write2_b32 v148, v34, v35 offset1:1
	ds_write2_b32 v148, v36, v37 offset0:2 offset1:3
	v_add_u32_e32 v148, 0x12480, v146
	ds_write2_b32 v148, v38, v39 offset1:1
	ds_write2_b32 v148, v40, v41 offset0:2 offset1:3
	v_add_u32_e32 v148, 0x14500, v146
	ds_write2_b32 v148, v42, v43 offset1:1
	ds_write2_b32 v148, v44, v45 offset0:2 offset1:3
	v_add_u32_e32 v148, 0x16580, v146
	ds_write2_b32 v148, v46, v47 offset1:1
	ds_write2_b32 v148, v48, v49 offset0:2 offset1:3
	v_add_u32_e32 v148, 0x18600, v146
	ds_write2_b32 v148, v50, v51 offset1:1
	ds_write2_b32 v148, v52, v53 offset0:2 offset1:3
	v_add_u32_e32 v148, 0x1a680, v146
	ds_write2_b32 v148, v54, v55 offset1:1
	ds_write2_b32 v148, v56, v57 offset0:2 offset1:3
	v_add_u32_e32 v148, 0x1c700, v146
	ds_write2_b32 v148, v58, v59 offset1:1
	ds_write2_b32 v148, v60, v61 offset0:2 offset1:3
	v_add_u32_e32 v148, 0x1e780, v146
	ds_write2_b32 v148, v62, v63 offset1:1
	ds_write2_b32 v148, v64, v65 offset0:2 offset1:3
	s_waitcnt lgkmcnt(0)
	s_add_i32 s16, s5, 544
	s_mul_i32 s18, s16, 1490
	s_lshr_b32 s18, s18, 16
	s_mul_i32 s17, s18, 44
	s_sub_i32 s17, s16, s17
	s_mul_i32 s17, s17, 262144
	s_lshl_b32 s18, s18, 8
	s_add_u32 s17, s17, s18
	s_add_u32 s20, s8, s17
	s_addc_u32 s21, s9, 0
	global_load_dwordx4 v[34:37], v157, s[20:21]
	global_load_dwordx4 v[38:41], v158, s[20:21]
	s_add_i32 s16, s5, 680
	s_add_i32 s19, s5, 544
	s_cmp_lt_u32 s16, 704
	s_cselect_b32 s16, s16, s19
	s_mul_i32 s18, s16, 1490
	s_lshr_b32 s18, s18, 16
	s_mul_i32 s17, s18, 44
	s_sub_i32 s17, s16, s17
	s_mul_i32 s17, s17, 262144
	s_lshl_b32 s18, s18, 8
	s_add_u32 s17, s17, s18
	s_add_u32 s20, s8, s17
	s_addc_u32 s21, s9, 0
	global_load_dwordx4 v[42:45], v157, s[20:21]
	global_load_dwordx4 v[46:49], v158, s[20:21]
	s_barrier
	v_add_u32_e32 v149, 0x10400, v147
	v_add_u32_e32 v150, 0x10800, v147
	ds_read2_b32 v[98:99], v149 offset1:65
	ds_read2_b32 v[100:101], v149 offset0:130 offset1:195
	ds_read2_b32 v[102:103], v150 offset0:4 offset1:69
	ds_read2_b32 v[104:105], v150 offset0:134 offset1:199
	v_add_u32_e32 v151, 0x14500, v147
	v_add_u32_e32 v152, 0x14900, v147
	ds_read2_b32 v[106:107], v151 offset1:65
	ds_read2_b32 v[108:109], v151 offset0:130 offset1:195
	ds_read2_b32 v[110:111], v152 offset0:4 offset1:69
	ds_read2_b32 v[112:113], v152 offset0:134 offset1:199
	v_add_u32_e32 v153, 0x18600, v147
	v_add_u32_e32 v154, 0x18a00, v147
	ds_read2_b32 v[114:115], v153 offset1:65
	ds_read2_b32 v[116:117], v153 offset0:130 offset1:195
	ds_read2_b32 v[118:119], v154 offset0:4 offset1:69
	ds_read2_b32 v[120:121], v154 offset0:134 offset1:199
	v_add_u32_e32 v155, 0x1c700, v147
	v_add_u32_e32 v156, 0x1cb00, v147
	ds_read2_b32 v[122:123], v155 offset1:65
	ds_read2_b32 v[124:125], v155 offset0:130 offset1:195
	ds_read2_b32 v[126:127], v156 offset0:4 offset1:69
	ds_read2_b32 v[128:129], v156 offset0:134 offset1:199
	s_add_i32 s16, s4, 544
	s_and_b32 s17, s16, 15
	s_lshr_b32 s18, s16, 4
	s_sub_i32 s23, s18, 44
	s_cmp_lt_u32 s18, 44
	s_cselect_b32 s22, s18, s23
	s_cselect_b32 s23, 0, 0x80
	s_lshr_b32 s18, s22, 1
	s_lshl_b32 s18, s18, 8
	s_and_b32 s22, s22, 1
	s_lshl_b32 s22, s22, 6
	s_add_i32 s22, s22, s18
	s_add_i32 s22, s22, s23
	s_mul_i32 s22, s22, 2048
	s_lshl_b32 s17, s17, 7
	s_add_u32 s22, s22, s17
	s_add_u32 s20, s10, s22
	s_addc_u32 s21, s11, 0
	s_waitcnt lgkmcnt(12)
	v_cvt_pk_bf16_f32 v130, v98, v99
	v_cvt_pk_bf16_f32 v131, v100, v101
	v_cvt_pk_bf16_f32 v132, v102, v103
	v_cvt_pk_bf16_f32 v133, v104, v105
	global_store_dwordx4 v161, v[130:133], s[20:21] sc1
	s_add_i32 s16, s4, 680
	s_and_b32 s17, s16, 15
	s_lshr_b32 s18, s16, 4
	s_sub_i32 s23, s18, 44
	s_cmp_lt_u32 s18, 44
	s_cselect_b32 s22, s18, s23
	s_cselect_b32 s23, 0, 0x80
	s_lshr_b32 s18, s22, 1
	s_lshl_b32 s18, s18, 8
	s_and_b32 s22, s22, 1
	s_lshl_b32 s22, s22, 6
	s_add_i32 s22, s22, s18
	s_add_i32 s22, s22, s23
	s_mul_i32 s22, s22, 2048
	s_lshl_b32 s17, s17, 7
	s_add_u32 s22, s22, s17
	s_add_u32 s20, s10, s22
	s_addc_u32 s21, s11, 0
	s_waitcnt lgkmcnt(8)
	v_cvt_pk_bf16_f32 v134, v106, v107
	v_cvt_pk_bf16_f32 v135, v108, v109
	v_cvt_pk_bf16_f32 v136, v110, v111
	v_cvt_pk_bf16_f32 v137, v112, v113
	global_store_dwordx4 v161, v[134:137], s[20:21] sc1
	s_add_i32 s16, s4, 816
	s_and_b32 s17, s16, 15
	s_lshr_b32 s18, s16, 4
	s_sub_i32 s23, s18, 44
	s_cmp_lt_u32 s18, 44
	s_cselect_b32 s22, s18, s23
	s_cselect_b32 s23, 0, 0x80
	s_lshr_b32 s18, s22, 1
	s_lshl_b32 s18, s18, 8
	s_and_b32 s22, s22, 1
	s_lshl_b32 s22, s22, 6
	s_add_i32 s22, s22, s18
	s_add_i32 s22, s22, s23
	s_mul_i32 s22, s22, 2048
	s_lshl_b32 s17, s17, 7
	s_add_u32 s22, s22, s17
	s_add_u32 s20, s10, s22
	s_addc_u32 s21, s11, 0
	s_waitcnt lgkmcnt(4)
	v_cvt_pk_bf16_f32 v138, v114, v115
	v_cvt_pk_bf16_f32 v139, v116, v117
	v_cvt_pk_bf16_f32 v140, v118, v119
	v_cvt_pk_bf16_f32 v141, v120, v121
	global_store_dwordx4 v161, v[138:141], s[20:21] sc1
	s_add_i32 s16, s4, 952
	s_and_b32 s17, s16, 15
	s_lshr_b32 s18, s16, 4
	s_sub_i32 s23, s18, 44
	s_cmp_lt_u32 s18, 44
	s_cselect_b32 s22, s18, s23
	s_cselect_b32 s23, 0, 0x80
	s_lshr_b32 s18, s22, 1
	s_lshl_b32 s18, s18, 8
	s_and_b32 s22, s22, 1
	s_lshl_b32 s22, s22, 6
	s_add_i32 s22, s22, s18
	s_add_i32 s22, s22, s23
	s_mul_i32 s22, s22, 2048
	s_lshl_b32 s17, s17, 7
	s_add_u32 s22, s22, s17
	s_add_u32 s20, s10, s22
	s_addc_u32 s21, s11, 0
	s_waitcnt lgkmcnt(0)
	v_cvt_pk_bf16_f32 v142, v122, v123
	v_cvt_pk_bf16_f32 v143, v124, v125
	v_cvt_pk_bf16_f32 v144, v126, v127
	v_cvt_pk_bf16_f32 v145, v128, v129
	global_store_dwordx4 v161, v[142:145], s[20:21] sc1
	s_waitcnt vmcnt(20)
	v_add_u32_e32 v148, 0x0, v146
	ds_write2_b32 v148, v66, v67 offset1:1
	ds_write2_b32 v148, v68, v69 offset0:2 offset1:3
	v_add_u32_e32 v148, 0x2080, v146
	ds_write2_b32 v148, v70, v71 offset1:1
	ds_write2_b32 v148, v72, v73 offset0:2 offset1:3
	v_add_u32_e32 v148, 0x4100, v146
	ds_write2_b32 v148, v74, v75 offset1:1
	ds_write2_b32 v148, v76, v77 offset0:2 offset1:3
	v_add_u32_e32 v148, 0x6180, v146
	ds_write2_b32 v148, v78, v79 offset1:1
	ds_write2_b32 v148, v80, v81 offset0:2 offset1:3
	v_add_u32_e32 v148, 0x8200, v146
	ds_write2_b32 v148, v82, v83 offset1:1
	ds_write2_b32 v148, v84, v85 offset0:2 offset1:3
	v_add_u32_e32 v148, 0xa280, v146
	ds_write2_b32 v148, v86, v87 offset1:1
	ds_write2_b32 v148, v88, v89 offset0:2 offset1:3
	s_waitcnt lgkmcnt(0)
	s_barrier
	v_add_u32_e32 v149, 0x0, v147
	v_add_u32_e32 v150, 0x400, v147
	ds_read2_b32 v[98:99], v149 offset1:65
	ds_read2_b32 v[100:101], v149 offset0:130 offset1:195
	ds_read2_b32 v[102:103], v150 offset0:4 offset1:69
	ds_read2_b32 v[104:105], v150 offset0:134 offset1:199
	v_add_u32_e32 v151, 0x4100, v147
	v_add_u32_e32 v152, 0x4500, v147
	ds_read2_b32 v[106:107], v151 offset1:65
	ds_read2_b32 v[108:109], v151 offset0:130 offset1:195
	ds_read2_b32 v[110:111], v152 offset0:4 offset1:69
	ds_read2_b32 v[112:113], v152 offset0:134 offset1:199
	v_add_u32_e32 v153, 0x8200, v147
	v_add_u32_e32 v154, 0x8600, v147
	ds_read2_b32 v[114:115], v153 offset1:65
	ds_read2_b32 v[116:117], v153 offset0:130 offset1:195
	ds_read2_b32 v[118:119], v154 offset0:4 offset1:69
	ds_read2_b32 v[120:121], v154 offset0:134 offset1:199
	s_add_i32 s16, s4, 1088
	s_and_b32 s17, s16, 15
	s_lshr_b32 s18, s16, 4
	s_sub_i32 s23, s18, 44
	s_cmp_lt_u32 s18, 44
	s_cselect_b32 s22, s18, s23
	s_cselect_b32 s23, 0, 0x80
	s_lshr_b32 s18, s22, 1
	s_lshl_b32 s18, s18, 8
	s_and_b32 s22, s22, 1
	s_lshl_b32 s22, s22, 6
	s_add_i32 s22, s22, s18
	s_add_i32 s22, s22, s23
	s_mul_i32 s22, s22, 2048
	s_lshl_b32 s17, s17, 7
	s_add_u32 s22, s22, s17
	s_add_u32 s20, s10, s22
	s_addc_u32 s21, s11, 0
	s_waitcnt lgkmcnt(8)
	v_cvt_pk_bf16_f32 v130, v98, v99
	v_cvt_pk_bf16_f32 v131, v100, v101
	v_cvt_pk_bf16_f32 v132, v102, v103
	v_cvt_pk_bf16_f32 v133, v104, v105
	global_store_dwordx4 v161, v[130:133], s[20:21] sc1
	s_add_i32 s16, s4, 1224
	s_and_b32 s17, s16, 15
	s_lshr_b32 s18, s16, 4
	s_sub_i32 s23, s18, 44
	s_cmp_lt_u32 s18, 44
	s_cselect_b32 s22, s18, s23
	s_cselect_b32 s23, 0, 0x80
	s_lshr_b32 s18, s22, 1
	s_lshl_b32 s18, s18, 8
	s_and_b32 s22, s22, 1
	s_lshl_b32 s22, s22, 6
	s_add_i32 s22, s22, s18
	s_add_i32 s22, s22, s23
	s_mul_i32 s22, s22, 2048
	s_lshl_b32 s17, s17, 7
	s_add_u32 s22, s22, s17
	s_add_u32 s20, s10, s22
	s_addc_u32 s21, s11, 0
	s_waitcnt lgkmcnt(4)
	v_cvt_pk_bf16_f32 v134, v106, v107
	v_cvt_pk_bf16_f32 v135, v108, v109
	v_cvt_pk_bf16_f32 v136, v110, v111
	v_cvt_pk_bf16_f32 v137, v112, v113
	global_store_dwordx4 v161, v[134:137], s[20:21] sc1
	s_add_i32 s16, s4, 1360
	s_and_b32 s17, s16, 15
	s_lshr_b32 s18, s16, 4
	s_sub_i32 s23, s18, 44
	s_cmp_lt_u32 s18, 44
	s_cselect_b32 s22, s18, s23
	s_cselect_b32 s23, 0, 0x80
	s_lshr_b32 s18, s22, 1
	s_lshl_b32 s18, s18, 8
	s_and_b32 s22, s22, 1
	s_lshl_b32 s22, s22, 6
	s_add_i32 s22, s22, s18
	s_add_i32 s22, s22, s23
	s_mul_i32 s22, s22, 2048
	s_lshl_b32 s17, s17, 7
	s_add_u32 s22, s22, s17
	s_add_u32 s20, s10, s22
	s_addc_u32 s21, s11, 0
	s_waitcnt lgkmcnt(0)
	v_cvt_pk_bf16_f32 v138, v114, v115
	v_cvt_pk_bf16_f32 v139, v116, v117
	v_cvt_pk_bf16_f32 v140, v118, v119
	v_cvt_pk_bf16_f32 v141, v120, v121
	s_cmp_ge_u32 s16, 1408
	s_cbranch_scc1 .Lcv4_1
	global_store_dwordx4 v161, v[138:141], s[20:21] sc1
.Lcv4_1:
	s_waitcnt vmcnt(14)
	v_add_u32_e32 v148, 0x10400, v146
	ds_write2_b32 v148, v2, v3 offset1:1
	ds_write2_b32 v148, v4, v5 offset0:2 offset1:3
	v_add_u32_e32 v148, 0x12480, v146
	ds_write2_b32 v148, v6, v7 offset1:1
	ds_write2_b32 v148, v8, v9 offset0:2 offset1:3
	v_add_u32_e32 v148, 0x14500, v146
	ds_write2_b32 v148, v10, v11 offset1:1
	ds_write2_b32 v148, v12, v13 offset0:2 offset1:3
	v_add_u32_e32 v148, 0x16580, v146
	ds_write2_b32 v148, v14, v15 offset1:1
	ds_write2_b32 v148, v16, v17 offset0:2 offset1:3
	v_add_u32_e32 v148, 0x18600, v146
	ds_write2_b32 v148, v18, v19 offset1:1
	ds_write2_b32 v148, v20, v21 offset0:2 offset1:3
	v_add_u32_e32 v148, 0x1a680, v146
	ds_write2_b32 v148, v22, v23 offset1:1
	ds_write2_b32 v148, v24, v25 offset0:2 offset1:3
	v_add_u32_e32 v148, 0x1c700, v146
	ds_write2_b32 v148, v26, v27 offset1:1
	ds_write2_b32 v148, v28, v29 offset0:2 offset1:3
	v_add_u32_e32 v148, 0x1e780, v146
	ds_write2_b32 v148, v30, v31 offset1:1
	ds_write2_b32 v148, v32, v33 offset0:2 offset1:3
	s_waitcnt lgkmcnt(0)
	s_barrier
	v_add_u32_e32 v149, 0x10400, v147
	v_add_u32_e32 v150, 0x10800, v147
	ds_read2_b32 v[98:99], v149 offset1:65
	ds_read2_b32 v[100:101], v149 offset0:130 offset1:195
	ds_read2_b32 v[102:103], v150 offset0:4 offset1:69
	ds_read2_b32 v[104:105], v150 offset0:134 offset1:199
	v_add_u32_e32 v151, 0x14500, v147
	v_add_u32_e32 v152, 0x14900, v147
	ds_read2_b32 v[106:107], v151 offset1:65
	ds_read2_b32 v[108:109], v151 offset0:130 offset1:195
	ds_read2_b32 v[110:111], v152 offset0:4 offset1:69
	ds_read2_b32 v[112:113], v152 offset0:134 offset1:199
	v_add_u32_e32 v153, 0x18600, v147
	v_add_u32_e32 v154, 0x18a00, v147
	ds_read2_b32 v[114:115], v153 offset1:65
	ds_read2_b32 v[116:117], v153 offset0:130 offset1:195
	ds_read2_b32 v[118:119], v154 offset0:4 offset1:69
	ds_read2_b32 v[120:121], v154 offset0:134 offset1:199
	v_add_u32_e32 v155, 0x1c700, v147
	v_add_u32_e32 v156, 0x1cb00, v147
	ds_read2_b32 v[122:123], v155 offset1:65
	ds_read2_b32 v[124:125], v155 offset0:130 offset1:195
	ds_read2_b32 v[126:127], v156 offset0:4 offset1:69
	ds_read2_b32 v[128:129], v156 offset0:134 offset1:199
	s_add_i32 s16, s5, 0
	s_mul_i32 s18, s16, 1490
	s_lshr_b32 s18, s18, 16
	s_mul_i32 s17, s18, 44
	s_sub_i32 s17, s16, s17
	s_lshl_b32 s22, s18, 6
	s_mul_i32 s22, s22, 5632
	s_lshl_b32 s17, s17, 7
	s_add_u32 s22, s22, s17
	s_add_u32 s20, s12, s22
	s_addc_u32 s21, s13, 0
	s_waitcnt lgkmcnt(12)
	v_cvt_pk_bf16_f32 v130, v98, v99
	v_cvt_pk_bf16_f32 v131, v100, v101
	v_cvt_pk_bf16_f32 v132, v102, v103
	v_cvt_pk_bf16_f32 v133, v104, v105
	global_store_dwordx4 v162, v[130:133], s[20:21] sc1
	s_add_i32 s16, s5, 136
	s_mul_i32 s18, s16, 1490
	s_lshr_b32 s18, s18, 16
	s_mul_i32 s17, s18, 44
	s_sub_i32 s17, s16, s17
	s_lshl_b32 s22, s18, 6
	s_mul_i32 s22, s22, 5632
	s_lshl_b32 s17, s17, 7
	s_add_u32 s22, s22, s17
	s_add_u32 s20, s12, s22
	s_addc_u32 s21, s13, 0
	s_waitcnt lgkmcnt(8)
	v_cvt_pk_bf16_f32 v134, v106, v107
	v_cvt_pk_bf16_f32 v135, v108, v109
	v_cvt_pk_bf16_f32 v136, v110, v111
	v_cvt_pk_bf16_f32 v137, v112, v113
	global_store_dwordx4 v162, v[134:137], s[20:21] sc1
	s_add_i32 s16, s5, 272
	s_mul_i32 s18, s16, 1490
	s_lshr_b32 s18, s18, 16
	s_mul_i32 s17, s18, 44
	s_sub_i32 s17, s16, s17
	s_lshl_b32 s22, s18, 6
	s_mul_i32 s22, s22, 5632
	s_lshl_b32 s17, s17, 7
	s_add_u32 s22, s22, s17
	s_add_u32 s20, s12, s22
	s_addc_u32 s21, s13, 0
	s_waitcnt lgkmcnt(4)
	v_cvt_pk_bf16_f32 v138, v114, v115
	v_cvt_pk_bf16_f32 v139, v116, v117
	v_cvt_pk_bf16_f32 v140, v118, v119
	v_cvt_pk_bf16_f32 v141, v120, v121
	global_store_dwordx4 v162, v[138:141], s[20:21] sc1
	s_add_i32 s16, s5, 408
	s_mul_i32 s18, s16, 1490
	s_lshr_b32 s18, s18, 16
	s_mul_i32 s17, s18, 44
	s_sub_i32 s17, s16, s17
	s_lshl_b32 s22, s18, 6
	s_mul_i32 s22, s22, 5632
	s_lshl_b32 s17, s17, 7
	s_add_u32 s22, s22, s17
	s_add_u32 s20, s12, s22
	s_addc_u32 s21, s13, 0
	s_waitcnt lgkmcnt(0)
	v_cvt_pk_bf16_f32 v142, v122, v123
	v_cvt_pk_bf16_f32 v143, v124, v125
	v_cvt_pk_bf16_f32 v144, v126, v127
	v_cvt_pk_bf16_f32 v145, v128, v129
	global_store_dwordx4 v162, v[142:145], s[20:21] sc1
	s_waitcnt vmcnt(10)
	v_add_u32_e32 v148, 0x0, v146
	ds_write2_b32 v148, v34, v35 offset1:1
	ds_write2_b32 v148, v36, v37 offset0:2 offset1:3
	v_add_u32_e32 v148, 0x2080, v146
	ds_write2_b32 v148, v38, v39 offset1:1
	ds_write2_b32 v148, v40, v41 offset0:2 offset1:3
	v_add_u32_e32 v148, 0x4100, v146
	ds_write2_b32 v148, v42, v43 offset1:1
	ds_write2_b32 v148, v44, v45 offset0:2 offset1:3
	v_add_u32_e32 v148, 0x6180, v146
	ds_write2_b32 v148, v46, v47 offset1:1
	ds_write2_b32 v148, v48, v49 offset0:2 offset1:3
	s_waitcnt lgkmcnt(0)
	s_barrier
	v_add_u32_e32 v149, 0x0, v147
	v_add_u32_e32 v150, 0x400, v147
	ds_read2_b32 v[98:99], v149 offset1:65
	ds_read2_b32 v[100:101], v149 offset0:130 offset1:195
	ds_read2_b32 v[102:103], v150 offset0:4 offset1:69
	ds_read2_b32 v[104:105], v150 offset0:134 offset1:199
	v_add_u32_e32 v151, 0x4100, v147
	v_add_u32_e32 v152, 0x4500, v147
	ds_read2_b32 v[106:107], v151 offset1:65
	ds_read2_b32 v[108:109], v151 offset0:130 offset1:195
	ds_read2_b32 v[110:111], v152 offset0:4 offset1:69
	ds_read2_b32 v[112:113], v152 offset0:134 offset1:199
	s_add_i32 s16, s5, 544
	s_mul_i32 s18, s16, 1490
	s_lshr_b32 s18, s18, 16
	s_mul_i32 s17, s18, 44
	s_sub_i32 s17, s16, s17
	s_lshl_b32 s22, s18, 6
	s_mul_i32 s22, s22, 5632
	s_lshl_b32 s17, s17, 7
	s_add_u32 s22, s22, s17
	s_add_u32 s20, s12, s22
	s_addc_u32 s21, s13, 0
	s_waitcnt lgkmcnt(4)
	v_cvt_pk_bf16_f32 v130, v98, v99
	v_cvt_pk_bf16_f32 v131, v100, v101
	v_cvt_pk_bf16_f32 v132, v102, v103
	v_cvt_pk_bf16_f32 v133, v104, v105
	global_store_dwordx4 v162, v[130:133], s[20:21] sc1
	s_add_i32 s16, s5, 680
	s_mul_i32 s18, s16, 1490
	s_lshr_b32 s18, s18, 16
	s_mul_i32 s17, s18, 44
	s_sub_i32 s17, s16, s17
	s_lshl_b32 s22, s18, 6
	s_mul_i32 s22, s22, 5632
	s_lshl_b32 s17, s17, 7
	s_add_u32 s22, s22, s17
	s_add_u32 s20, s12, s22
	s_addc_u32 s21, s13, 0
	s_waitcnt lgkmcnt(0)
	v_cvt_pk_bf16_f32 v134, v106, v107
	v_cvt_pk_bf16_f32 v135, v108, v109
	v_cvt_pk_bf16_f32 v136, v110, v111
	v_cvt_pk_bf16_f32 v137, v112, v113
	s_cmp_ge_u32 s16, 704
	s_cbranch_scc1 .Lcv4_2
	global_store_dwordx4 v162, v[134:137], s[20:21] sc1
.Lcv4_2:
.LBB0_1558:
	s_cmp_lt_i32 s59, 12
	s_waitcnt lgkmcnt(0)
	s_barrier
	s_cbranch_scc1 .LBB0_1612
	s_waitcnt vmcnt(0)
	s_barrier
	s_and_saveexec_b64 s[2:3], s[0:1]
	s_cbranch_execz .LBB0_1611
	s_waitcnt vmcnt(0) lgkmcnt(0)
	v_mov_b32_e32 v241, 0
